# final RMSNorm phase rewritten by hand: all loads of a 4-row trip issued together, next trip prefetched, one counted wait per trip (f32 math unchanged)
# speedup vs baseline: 1.1814x; 1.1814x over previous
.LBB0_78:
	v_readlane_b32 s0, v255, 24
	s_cmp_lt_i32 s0, 8
	s_cselect_b32 s0, s0, 0
	s_ashr_i32 s1, s0, 31
	s_lshl_b64 s[0:1], s[0:1], 2
	s_getpc_b64 s[2:3]
	s_add_u32 s2, s2, __const._Z10hybrid_fwd6Params.prog@rel32@lo+4
	s_addc_u32 s3, s3, __const._Z10hybrid_fwd6Params.prog@rel32@hi+12
	s_add_u32 s0, s2, s0
	s_addc_u32 s1, s3, s1
	s_load_dword s0, s[0:1], 0x0
	s_waitcnt lgkmcnt(0)
	v_writelane_b32 v255, s0, 25
	s_cmp_lt_i32 s0, 4
	s_mov_b64 s[0:1], -1
	s_cbranch_scc1 .LBB0_192
	v_readlane_b32 s0, v255, 25
	s_cmp_lt_i32 s0, 7
	s_mov_b64 s[0:1], -1
	s_cbranch_scc1 .LBB0_121
	v_readlane_b32 s0, v255, 25
	s_cmp_lt_i32 s0, 8
	s_mov_b64 s[0:1], -1
	s_cbranch_scc1 .LBB0_87
	v_readlane_b32 s0, v255, 25
	s_cmp_eq_u32 s0, 8
	s_cbranch_scc0 .LBB0_86
	v_and_b32_e32 v16, 63, v179
	v_lshrrev_b32_e32 v17, 6, v179
	v_readlane_b32 s0, v253, 28
	v_readlane_b32 s44, v252, 4
	v_readfirstlane_b32 s1, v17
	v_readlane_b32 s45, v252, 5
	v_readlane_b32 s46, v252, 6
	v_readlane_b32 s47, v252, 7
	s_load_dword s43, s[74:75], 0x0
	s_mov_b64 s[38:39], exec
	v_lshlrev_b32_e32 v18, 5, v16
	v_lshlrev_b32_e32 v19, 4, v16
	v_and_b32_e32 v20, 15, v16
	v_lshlrev_b32_e32 v20, 4, v20
	v_mov_b32_e32 v21, 0x3727c5ac
	s_lshl_b32 s1, s1, 2
	s_add_i32 s41, s0, s1
	s_mov_b32 s6, 0x3a800000
	s_cmp_lt_i32 s41, 0x8000
	s_cbranch_scc0 .Lfn_done
	global_load_dwordx4 v[0:3], v18, s[44:45] offset:16
	global_load_dwordx4 v[4:7], v18, s[44:45]
	global_load_dwordx4 v[8:11], v18, s[44:45] offset:2064
	global_load_dwordx4 v[12:15], v18, s[44:45] offset:2048
	s_lshl_b32 s1, s41, 6
	v_add_u32_e32 v116, s1, v20
	s_lshl_b32 s1, s41, 11
	v_add_u32_e32 v117, s1, v19
	v_add_u32_e32 v118, 0x1000, v117
	global_load_dwordx4 v[24:27], v116, s[62:63]
	global_load_dwordx4 v[32:35], v117, s[64:65]
	global_load_dwordx4 v[36:39], v117, s[64:65] offset:1024
	global_load_dwordx4 v[40:43], v117, s[64:65] offset:2048
	global_load_dwordx4 v[44:47], v117, s[64:65] offset:3072
	global_load_dwordx4 v[48:51], v118, s[64:65]
	global_load_dwordx4 v[52:55], v118, s[64:65] offset:1024
	global_load_dwordx4 v[56:59], v118, s[64:65] offset:2048
	global_load_dwordx4 v[60:63], v118, s[64:65] offset:3072
	s_waitcnt lgkmcnt(0)
	s_lshl_b32 s43, s43, 5
	s_add_i32 s39, s41, s43
	s_cmp_lt_i32 s39, 0x8000
	s_cbranch_scc0 .Lfn_first_nol
	s_lshl_b32 s1, s39, 6
	v_add_u32_e32 v116, s1, v20
	s_lshl_b32 s1, s39, 11
	v_add_u32_e32 v117, s1, v19
	v_add_u32_e32 v118, 0x1000, v117
	global_load_dwordx4 v[28:31], v116, s[62:63]
	global_load_dwordx4 v[64:67], v117, s[64:65]
	global_load_dwordx4 v[68:71], v117, s[64:65] offset:1024
	global_load_dwordx4 v[72:75], v117, s[64:65] offset:2048
	global_load_dwordx4 v[76:79], v117, s[64:65] offset:3072
	global_load_dwordx4 v[80:83], v118, s[64:65]
	global_load_dwordx4 v[84:87], v118, s[64:65] offset:1024
	global_load_dwordx4 v[88:91], v118, s[64:65] offset:2048
	global_load_dwordx4 v[92:95], v118, s[64:65] offset:3072
	s_waitcnt vmcnt(9)
	s_branch .Lfn_comp_A
.Lfn_first_nol:
	s_waitcnt vmcnt(0)
	s_branch .Lfn_comp_A
.Lfn_step_A:
	s_add_i32 s39, s41, s43
	s_cmp_lt_i32 s39, 0x8000
	s_cbranch_scc0 .Lfn_nol_A
	s_lshl_b32 s1, s39, 6
	v_add_u32_e32 v116, s1, v20
	s_lshl_b32 s1, s39, 11
	v_add_u32_e32 v117, s1, v19
	v_add_u32_e32 v118, 0x1000, v117
	global_load_dwordx4 v[28:31], v116, s[62:63]
	global_load_dwordx4 v[64:67], v117, s[64:65]
	global_load_dwordx4 v[68:71], v117, s[64:65] offset:1024
	global_load_dwordx4 v[72:75], v117, s[64:65] offset:2048
	global_load_dwordx4 v[76:79], v117, s[64:65] offset:3072
	global_load_dwordx4 v[80:83], v118, s[64:65]
	global_load_dwordx4 v[84:87], v118, s[64:65] offset:1024
	global_load_dwordx4 v[88:91], v118, s[64:65] offset:2048
	global_load_dwordx4 v[92:95], v118, s[64:65] offset:3072
	s_waitcnt vmcnt(25)
	s_branch .Lfn_comp_A
.Lfn_nol_A:
	s_waitcnt vmcnt(16)
.Lfn_comp_A:
	v_add_f32_dpp v108, v24, v24 quad_perm:[1,0,3,2] row_mask:0xf bank_mask:0xf
	v_add_f32_dpp v109, v25, v25 quad_perm:[1,0,3,2] row_mask:0xf bank_mask:0xf
	v_add_f32_dpp v110, v26, v26 quad_perm:[1,0,3,2] row_mask:0xf bank_mask:0xf
	v_add_f32_dpp v111, v27, v27 quad_perm:[1,0,3,2] row_mask:0xf bank_mask:0xf
	v_add_f32_dpp v112, v108, v108 quad_perm:[2,3,0,1] row_mask:0xf bank_mask:0xf
	v_add_f32_dpp v113, v109, v109 quad_perm:[2,3,0,1] row_mask:0xf bank_mask:0xf
	v_add_f32_dpp v114, v110, v110 quad_perm:[2,3,0,1] row_mask:0xf bank_mask:0xf
	v_add_f32_dpp v115, v111, v111 quad_perm:[2,3,0,1] row_mask:0xf bank_mask:0xf
	v_add_f32_e32 v108, v112, v113
	v_add_f32_e32 v108, v108, v114
	v_add_f32_e32 v108, v108, v115
	v_fma_f32 v108, v108, s6, v21
	v_rsq_f32_e32 v108, v108
	s_lshl_b32 s1, s41, 12
	v_add_u32_e32 v120, s1, v18
	v_add_u32_e32 v121, 0x1000, v120
	v_readlane_b32 s0, v108, 0
	v_readlane_b32 s38, v108, 4
	v_readlane_b32 s40, v108, 8
	v_readlane_b32 s42, v108, 12
	v_add_u32_e32 v122, 0x2000, v120
	v_add_u32_e32 v123, 0x3000, v120
	v_lshlrev_b32_e32 v96, 16, v32
	v_and_b32_e32 v97, 0xffff0000, v32
	v_lshlrev_b32_e32 v98, 16, v33
	v_and_b32_e32 v99, 0xffff0000, v33
	v_lshlrev_b32_e32 v100, 16, v34
	v_and_b32_e32 v101, 0xffff0000, v34
	v_lshlrev_b32_e32 v102, 16, v35
	v_and_b32_e32 v103, 0xffff0000, v35
	v_pk_mul_f32 v[96:97], s[0:1], v[96:97] op_sel_hi:[0,1]
	v_pk_mul_f32 v[98:99], s[0:1], v[98:99] op_sel_hi:[0,1]
	v_pk_mul_f32 v[100:101], s[0:1], v[100:101] op_sel_hi:[0,1]
	v_pk_mul_f32 v[102:103], s[0:1], v[102:103] op_sel_hi:[0,1]
	v_pk_mul_f32 v[96:97], v[4:5], v[96:97]
	v_pk_mul_f32 v[98:99], v[6:7], v[98:99]
	v_pk_mul_f32 v[100:101], v[0:1], v[100:101]
	v_pk_mul_f32 v[102:103], v[2:3], v[102:103]
	global_store_dwordx4 v120, v[96:99], s[46:47]
	global_store_dwordx4 v120, v[100:103], s[46:47] offset:16
	v_lshlrev_b32_e32 v104, 16, v36
	v_and_b32_e32 v105, 0xffff0000, v36
	v_lshlrev_b32_e32 v106, 16, v37
	v_and_b32_e32 v107, 0xffff0000, v37
	v_lshlrev_b32_e32 v108, 16, v38
	v_and_b32_e32 v109, 0xffff0000, v38
	v_lshlrev_b32_e32 v110, 16, v39
	v_and_b32_e32 v111, 0xffff0000, v39
	v_pk_mul_f32 v[104:105], s[0:1], v[104:105] op_sel_hi:[0,1]
	v_pk_mul_f32 v[106:107], s[0:1], v[106:107] op_sel_hi:[0,1]
	v_pk_mul_f32 v[108:109], s[0:1], v[108:109] op_sel_hi:[0,1]
	v_pk_mul_f32 v[110:111], s[0:1], v[110:111] op_sel_hi:[0,1]
	v_pk_mul_f32 v[104:105], v[12:13], v[104:105]
	v_pk_mul_f32 v[106:107], v[14:15], v[106:107]
	v_pk_mul_f32 v[108:109], v[8:9], v[108:109]
	v_pk_mul_f32 v[110:111], v[10:11], v[110:111]
	global_store_dwordx4 v120, v[104:107], s[46:47] offset:2048
	global_store_dwordx4 v120, v[108:111], s[46:47] offset:2064
	v_lshlrev_b32_e32 v96, 16, v40
	v_and_b32_e32 v97, 0xffff0000, v40
	v_lshlrev_b32_e32 v98, 16, v41
	v_and_b32_e32 v99, 0xffff0000, v41
	v_lshlrev_b32_e32 v100, 16, v42
	v_and_b32_e32 v101, 0xffff0000, v42
	v_lshlrev_b32_e32 v102, 16, v43
	v_and_b32_e32 v103, 0xffff0000, v43
	v_pk_mul_f32 v[96:97], s[38:39], v[96:97] op_sel_hi:[0,1]
	v_pk_mul_f32 v[98:99], s[38:39], v[98:99] op_sel_hi:[0,1]
	v_pk_mul_f32 v[100:101], s[38:39], v[100:101] op_sel_hi:[0,1]
	v_pk_mul_f32 v[102:103], s[38:39], v[102:103] op_sel_hi:[0,1]
	v_pk_mul_f32 v[96:97], v[4:5], v[96:97]
	v_pk_mul_f32 v[98:99], v[6:7], v[98:99]
	v_pk_mul_f32 v[100:101], v[0:1], v[100:101]
	v_pk_mul_f32 v[102:103], v[2:3], v[102:103]
	global_store_dwordx4 v121, v[96:99], s[46:47]
	global_store_dwordx4 v121, v[100:103], s[46:47] offset:16
	v_lshlrev_b32_e32 v104, 16, v44
	v_and_b32_e32 v105, 0xffff0000, v44
	v_lshlrev_b32_e32 v106, 16, v45
	v_and_b32_e32 v107, 0xffff0000, v45
	v_lshlrev_b32_e32 v108, 16, v46
	v_and_b32_e32 v109, 0xffff0000, v46
	v_lshlrev_b32_e32 v110, 16, v47
	v_and_b32_e32 v111, 0xffff0000, v47
	v_pk_mul_f32 v[104:105], s[38:39], v[104:105] op_sel_hi:[0,1]
	v_pk_mul_f32 v[106:107], s[38:39], v[106:107] op_sel_hi:[0,1]
	v_pk_mul_f32 v[108:109], s[38:39], v[108:109] op_sel_hi:[0,1]
	v_pk_mul_f32 v[110:111], s[38:39], v[110:111] op_sel_hi:[0,1]
	v_pk_mul_f32 v[104:105], v[12:13], v[104:105]
	v_pk_mul_f32 v[106:107], v[14:15], v[106:107]
	v_pk_mul_f32 v[108:109], v[8:9], v[108:109]
	v_pk_mul_f32 v[110:111], v[10:11], v[110:111]
	global_store_dwordx4 v121, v[104:107], s[46:47] offset:2048
	global_store_dwordx4 v121, v[108:111], s[46:47] offset:2064
	v_lshlrev_b32_e32 v96, 16, v48
	v_and_b32_e32 v97, 0xffff0000, v48
	v_lshlrev_b32_e32 v98, 16, v49
	v_and_b32_e32 v99, 0xffff0000, v49
	v_lshlrev_b32_e32 v100, 16, v50
	v_and_b32_e32 v101, 0xffff0000, v50
	v_lshlrev_b32_e32 v102, 16, v51
	v_and_b32_e32 v103, 0xffff0000, v51
	v_pk_mul_f32 v[96:97], s[40:41], v[96:97] op_sel_hi:[0,1]
	v_pk_mul_f32 v[98:99], s[40:41], v[98:99] op_sel_hi:[0,1]
	v_pk_mul_f32 v[100:101], s[40:41], v[100:101] op_sel_hi:[0,1]
	v_pk_mul_f32 v[102:103], s[40:41], v[102:103] op_sel_hi:[0,1]
	v_pk_mul_f32 v[96:97], v[4:5], v[96:97]
	v_pk_mul_f32 v[98:99], v[6:7], v[98:99]
	v_pk_mul_f32 v[100:101], v[0:1], v[100:101]
	v_pk_mul_f32 v[102:103], v[2:3], v[102:103]
	global_store_dwordx4 v122, v[96:99], s[46:47]
	global_store_dwordx4 v122, v[100:103], s[46:47] offset:16
	v_lshlrev_b32_e32 v104, 16, v52
	v_and_b32_e32 v105, 0xffff0000, v52
	v_lshlrev_b32_e32 v106, 16, v53
	v_and_b32_e32 v107, 0xffff0000, v53
	v_lshlrev_b32_e32 v108, 16, v54
	v_and_b32_e32 v109, 0xffff0000, v54
	v_lshlrev_b32_e32 v110, 16, v55
	v_and_b32_e32 v111, 0xffff0000, v55
	v_pk_mul_f32 v[104:105], s[40:41], v[104:105] op_sel_hi:[0,1]
	v_pk_mul_f32 v[106:107], s[40:41], v[106:107] op_sel_hi:[0,1]
	v_pk_mul_f32 v[108:109], s[40:41], v[108:109] op_sel_hi:[0,1]
	v_pk_mul_f32 v[110:111], s[40:41], v[110:111] op_sel_hi:[0,1]
	v_pk_mul_f32 v[104:105], v[12:13], v[104:105]
	v_pk_mul_f32 v[106:107], v[14:15], v[106:107]
	v_pk_mul_f32 v[108:109], v[8:9], v[108:109]
	v_pk_mul_f32 v[110:111], v[10:11], v[110:111]
	global_store_dwordx4 v122, v[104:107], s[46:47] offset:2048
	global_store_dwordx4 v122, v[108:111], s[46:47] offset:2064
	v_lshlrev_b32_e32 v96, 16, v56
	v_and_b32_e32 v97, 0xffff0000, v56
	v_lshlrev_b32_e32 v98, 16, v57
	v_and_b32_e32 v99, 0xffff0000, v57
	v_lshlrev_b32_e32 v100, 16, v58
	v_and_b32_e32 v101, 0xffff0000, v58
	v_lshlrev_b32_e32 v102, 16, v59
	v_and_b32_e32 v103, 0xffff0000, v59
	v_pk_mul_f32 v[96:97], s[42:43], v[96:97] op_sel_hi:[0,1]
	v_pk_mul_f32 v[98:99], s[42:43], v[98:99] op_sel_hi:[0,1]
	v_pk_mul_f32 v[100:101], s[42:43], v[100:101] op_sel_hi:[0,1]
	v_pk_mul_f32 v[102:103], s[42:43], v[102:103] op_sel_hi:[0,1]
	v_pk_mul_f32 v[96:97], v[4:5], v[96:97]
	v_pk_mul_f32 v[98:99], v[6:7], v[98:99]
	v_pk_mul_f32 v[100:101], v[0:1], v[100:101]
	v_pk_mul_f32 v[102:103], v[2:3], v[102:103]
	global_store_dwordx4 v123, v[96:99], s[46:47]
	global_store_dwordx4 v123, v[100:103], s[46:47] offset:16
	v_lshlrev_b32_e32 v104, 16, v60
	v_and_b32_e32 v105, 0xffff0000, v60
	v_lshlrev_b32_e32 v106, 16, v61
	v_and_b32_e32 v107, 0xffff0000, v61
	v_lshlrev_b32_e32 v108, 16, v62
	v_and_b32_e32 v109, 0xffff0000, v62
	v_lshlrev_b32_e32 v110, 16, v63
	v_and_b32_e32 v111, 0xffff0000, v63
	v_pk_mul_f32 v[104:105], s[42:43], v[104:105] op_sel_hi:[0,1]
	v_pk_mul_f32 v[106:107], s[42:43], v[106:107] op_sel_hi:[0,1]
	v_pk_mul_f32 v[108:109], s[42:43], v[108:109] op_sel_hi:[0,1]
	v_pk_mul_f32 v[110:111], s[42:43], v[110:111] op_sel_hi:[0,1]
	v_pk_mul_f32 v[104:105], v[12:13], v[104:105]
	v_pk_mul_f32 v[106:107], v[14:15], v[106:107]
	v_pk_mul_f32 v[108:109], v[8:9], v[108:109]
	v_pk_mul_f32 v[110:111], v[10:11], v[110:111]
	global_store_dwordx4 v123, v[104:107], s[46:47] offset:2048
	global_store_dwordx4 v123, v[108:111], s[46:47] offset:2064
	s_mov_b32 s41, s39
	s_cmp_lt_i32 s41, 0x8000
	s_cbranch_scc0 .Lfn_done
.Lfn_step_B:
	s_add_i32 s39, s41, s43
	s_cmp_lt_i32 s39, 0x8000
	s_cbranch_scc0 .Lfn_nol_B
	s_lshl_b32 s1, s39, 6
	v_add_u32_e32 v116, s1, v20
	s_lshl_b32 s1, s39, 11
	v_add_u32_e32 v117, s1, v19
	v_add_u32_e32 v118, 0x1000, v117
	global_load_dwordx4 v[24:27], v116, s[62:63]
	global_load_dwordx4 v[32:35], v117, s[64:65]
	global_load_dwordx4 v[36:39], v117, s[64:65] offset:1024
	global_load_dwordx4 v[40:43], v117, s[64:65] offset:2048
	global_load_dwordx4 v[44:47], v117, s[64:65] offset:3072
	global_load_dwordx4 v[48:51], v118, s[64:65]
	global_load_dwordx4 v[52:55], v118, s[64:65] offset:1024
	global_load_dwordx4 v[56:59], v118, s[64:65] offset:2048
	global_load_dwordx4 v[60:63], v118, s[64:65] offset:3072
	s_waitcnt vmcnt(25)
	s_branch .Lfn_comp_B

.Lfn_comp_B:
	v_add_f32_dpp v108, v28, v28 quad_perm:[1,0,3,2] row_mask:0xf bank_mask:0xf
	v_add_f32_dpp v109, v29, v29 quad_perm:[1,0,3,2] row_mask:0xf bank_mask:0xf
	v_add_f32_dpp v110, v30, v30 quad_perm:[1,0,3,2] row_mask:0xf bank_mask:0xf
	v_add_f32_dpp v111, v31, v31 quad_perm:[1,0,3,2] row_mask:0xf bank_mask:0xf
	v_add_f32_dpp v112, v108, v108 quad_perm:[2,3,0,1] row_mask:0xf bank_mask:0xf
	v_add_f32_dpp v113, v109, v109 quad_perm:[2,3,0,1] row_mask:0xf bank_mask:0xf
	v_add_f32_dpp v114, v110, v110 quad_perm:[2,3,0,1] row_mask:0xf bank_mask:0xf
	v_add_f32_dpp v115, v111, v111 quad_perm:[2,3,0,1] row_mask:0xf bank_mask:0xf
	v_add_f32_e32 v108, v112, v113
	v_add_f32_e32 v108, v108, v114
	v_add_f32_e32 v108, v108, v115
	v_fma_f32 v108, v108, s6, v21
	v_rsq_f32_e32 v108, v108
	s_lshl_b32 s1, s41, 12
	v_add_u32_e32 v120, s1, v18
	v_add_u32_e32 v121, 0x1000, v120
	v_readlane_b32 s0, v108, 0
	v_readlane_b32 s38, v108, 4
	v_readlane_b32 s40, v108, 8
	v_readlane_b32 s42, v108, 12
	v_add_u32_e32 v122, 0x2000, v120
	v_add_u32_e32 v123, 0x3000, v120
	v_lshlrev_b32_e32 v96, 16, v64
	v_and_b32_e32 v97, 0xffff0000, v64
	v_lshlrev_b32_e32 v98, 16, v65
	v_and_b32_e32 v99, 0xffff0000, v65
	v_lshlrev_b32_e32 v100, 16, v66
	v_and_b32_e32 v101, 0xffff0000, v66
	v_lshlrev_b32_e32 v102, 16, v67
	v_and_b32_e32 v103, 0xffff0000, v67
	v_pk_mul_f32 v[96:97], s[0:1], v[96:97] op_sel_hi:[0,1]
	v_pk_mul_f32 v[98:99], s[0:1], v[98:99] op_sel_hi:[0,1]
	v_pk_mul_f32 v[100:101], s[0:1], v[100:101] op_sel_hi:[0,1]
	v_pk_mul_f32 v[102:103], s[0:1], v[102:103] op_sel_hi:[0,1]
	v_pk_mul_f32 v[96:97], v[4:5], v[96:97]
	v_pk_mul_f32 v[98:99], v[6:7], v[98:99]
	v_pk_mul_f32 v[100:101], v[0:1], v[100:101]
	v_pk_mul_f32 v[102:103], v[2:3], v[102:103]
	global_store_dwordx4 v120, v[96:99], s[46:47]
	global_store_dwordx4 v120, v[100:103], s[46:47] offset:16
	v_lshlrev_b32_e32 v104, 16, v68
	v_and_b32_e32 v105, 0xffff0000, v68
	v_lshlrev_b32_e32 v106, 16, v69
	v_and_b32_e32 v107, 0xffff0000, v69
	v_lshlrev_b32_e32 v108, 16, v70
	v_and_b32_e32 v109, 0xffff0000, v70
	v_lshlrev_b32_e32 v110, 16, v71
	v_and_b32_e32 v111, 0xffff0000, v71
	v_pk_mul_f32 v[104:105], s[0:1], v[104:105] op_sel_hi:[0,1]
	v_pk_mul_f32 v[106:107], s[0:1], v[106:107] op_sel_hi:[0,1]
	v_pk_mul_f32 v[108:109], s[0:1], v[108:109] op_sel_hi:[0,1]
	v_pk_mul_f32 v[110:111], s[0:1], v[110:111] op_sel_hi:[0,1]
	v_pk_mul_f32 v[104:105], v[12:13], v[104:105]
	v_pk_mul_f32 v[106:107], v[14:15], v[106:107]
	v_pk_mul_f32 v[108:109], v[8:9], v[108:109]
	v_pk_mul_f32 v[110:111], v[10:11], v[110:111]
	global_store_dwordx4 v120, v[104:107], s[46:47] offset:2048
	global_store_dwordx4 v120, v[108:111], s[46:47] offset:2064
	v_lshlrev_b32_e32 v96, 16, v72
	v_and_b32_e32 v97, 0xffff0000, v72
	v_lshlrev_b32_e32 v98, 16, v73
	v_and_b32_e32 v99, 0xffff0000, v73
	v_lshlrev_b32_e32 v100, 16, v74
	v_and_b32_e32 v101, 0xffff0000, v74
	v_lshlrev_b32_e32 v102, 16, v75
	v_and_b32_e32 v103, 0xffff0000, v75
	v_pk_mul_f32 v[96:97], s[38:39], v[96:97] op_sel_hi:[0,1]
	v_pk_mul_f32 v[98:99], s[38:39], v[98:99] op_sel_hi:[0,1]
	v_pk_mul_f32 v[100:101], s[38:39], v[100:101] op_sel_hi:[0,1]
	v_pk_mul_f32 v[102:103], s[38:39], v[102:103] op_sel_hi:[0,1]
	v_pk_mul_f32 v[96:97], v[4:5], v[96:97]
	v_pk_mul_f32 v[98:99], v[6:7], v[98:99]
	v_pk_mul_f32 v[100:101], v[0:1], v[100:101]
	v_pk_mul_f32 v[102:103], v[2:3], v[102:103]
	global_store_dwordx4 v121, v[96:99], s[46:47]
	global_store_dwordx4 v121, v[100:103], s[46:47] offset:16
	v_lshlrev_b32_e32 v104, 16, v76
	v_and_b32_e32 v105, 0xffff0000, v76
	v_lshlrev_b32_e32 v106, 16, v77
	v_and_b32_e32 v107, 0xffff0000, v77
	v_lshlrev_b32_e32 v108, 16, v78
	v_and_b32_e32 v109, 0xffff0000, v78
	v_lshlrev_b32_e32 v110, 16, v79
	v_and_b32_e32 v111, 0xffff0000, v79
	v_pk_mul_f32 v[104:105], s[38:39], v[104:105] op_sel_hi:[0,1]
	v_pk_mul_f32 v[106:107], s[38:39], v[106:107] op_sel_hi:[0,1]
	v_pk_mul_f32 v[108:109], s[38:39], v[108:109] op_sel_hi:[0,1]
	v_pk_mul_f32 v[110:111], s[38:39], v[110:111] op_sel_hi:[0,1]
	v_pk_mul_f32 v[104:105], v[12:13], v[104:105]
	v_pk_mul_f32 v[106:107], v[14:15], v[106:107]
	v_pk_mul_f32 v[108:109], v[8:9], v[108:109]
	v_pk_mul_f32 v[110:111], v[10:11], v[110:111]
	global_store_dwordx4 v121, v[104:107], s[46:47] offset:2048
	global_store_dwordx4 v121, v[108:111], s[46:47] offset:2064
	v_lshlrev_b32_e32 v96, 16, v80
	v_and_b32_e32 v97, 0xffff0000, v80
	v_lshlrev_b32_e32 v98, 16, v81
	v_and_b32_e32 v99, 0xffff0000, v81
	v_lshlrev_b32_e32 v100, 16, v82
	v_and_b32_e32 v101, 0xffff0000, v82
	v_lshlrev_b32_e32 v102, 16, v83
	v_and_b32_e32 v103, 0xffff0000, v83
	v_pk_mul_f32 v[96:97], s[40:41], v[96:97] op_sel_hi:[0,1]
	v_pk_mul_f32 v[98:99], s[40:41], v[98:99] op_sel_hi:[0,1]
	v_pk_mul_f32 v[100:101], s[40:41], v[100:101] op_sel_hi:[0,1]
	v_pk_mul_f32 v[102:103], s[40:41], v[102:103] op_sel_hi:[0,1]
	v_pk_mul_f32 v[96:97], v[4:5], v[96:97]
	v_pk_mul_f32 v[98:99], v[6:7], v[98:99]
	v_pk_mul_f32 v[100:101], v[0:1], v[100:101]
	v_pk_mul_f32 v[102:103], v[2:3], v[102:103]
	global_store_dwordx4 v122, v[96:99], s[46:47]
	global_store_dwordx4 v122, v[100:103], s[46:47] offset:16
	v_lshlrev_b32_e32 v104, 16, v84
	v_and_b32_e32 v105, 0xffff0000, v84
	v_lshlrev_b32_e32 v106, 16, v85
	v_and_b32_e32 v107, 0xffff0000, v85
	v_lshlrev_b32_e32 v108, 16, v86
	v_and_b32_e32 v109, 0xffff0000, v86
	v_lshlrev_b32_e32 v110, 16, v87
	v_and_b32_e32 v111, 0xffff0000, v87
	v_pk_mul_f32 v[104:105], s[40:41], v[104:105] op_sel_hi:[0,1]
	v_pk_mul_f32 v[106:107], s[40:41], v[106:107] op_sel_hi:[0,1]
	v_pk_mul_f32 v[108:109], s[40:41], v[108:109] op_sel_hi:[0,1]
	v_pk_mul_f32 v[110:111], s[40:41], v[110:111] op_sel_hi:[0,1]
	v_pk_mul_f32 v[104:105], v[12:13], v[104:105]
	v_pk_mul_f32 v[106:107], v[14:15], v[106:107]
	v_pk_mul_f32 v[108:109], v[8:9], v[108:109]
	v_pk_mul_f32 v[110:111], v[10:11], v[110:111]
	global_store_dwordx4 v122, v[104:107], s[46:47] offset:2048
	global_store_dwordx4 v122, v[108:111], s[46:47] offset:2064
	v_lshlrev_b32_e32 v96, 16, v88
	v_and_b32_e32 v97, 0xffff0000, v88
	v_lshlrev_b32_e32 v98, 16, v89
	v_and_b32_e32 v99, 0xffff0000, v89
	v_lshlrev_b32_e32 v100, 16, v90
	v_and_b32_e32 v101, 0xffff0000, v90
	v_lshlrev_b32_e32 v102, 16, v91
	v_and_b32_e32 v103, 0xffff0000, v91
	v_pk_mul_f32 v[96:97], s[42:43], v[96:97] op_sel_hi:[0,1]
	v_pk_mul_f32 v[98:99], s[42:43], v[98:99] op_sel_hi:[0,1]
	v_pk_mul_f32 v[100:101], s[42:43], v[100:101] op_sel_hi:[0,1]
	v_pk_mul_f32 v[102:103], s[42:43], v[102:103] op_sel_hi:[0,1]
	v_pk_mul_f32 v[96:97], v[4:5], v[96:97]
	v_pk_mul_f32 v[98:99], v[6:7], v[98:99]
	v_pk_mul_f32 v[100:101], v[0:1], v[100:101]
	v_pk_mul_f32 v[102:103], v[2:3], v[102:103]
	global_store_dwordx4 v123, v[96:99], s[46:47]
	global_store_dwordx4 v123, v[100:103], s[46:47] offset:16
	v_lshlrev_b32_e32 v104, 16, v92
	v_and_b32_e32 v105, 0xffff0000, v92
	v_lshlrev_b32_e32 v106, 16, v93
	v_and_b32_e32 v107, 0xffff0000, v93
	v_lshlrev_b32_e32 v108, 16, v94
	v_and_b32_e32 v109, 0xffff0000, v94
	v_lshlrev_b32_e32 v110, 16, v95
	v_and_b32_e32 v111, 0xffff0000, v95
	v_pk_mul_f32 v[104:105], s[42:43], v[104:105] op_sel_hi:[0,1]
	v_pk_mul_f32 v[106:107], s[42:43], v[106:107] op_sel_hi:[0,1]
	v_pk_mul_f32 v[108:109], s[42:43], v[108:109] op_sel_hi:[0,1]
	v_pk_mul_f32 v[110:111], s[42:43], v[110:111] op_sel_hi:[0,1]
	v_pk_mul_f32 v[104:105], v[12:13], v[104:105]
	v_pk_mul_f32 v[106:107], v[14:15], v[106:107]
	v_pk_mul_f32 v[108:109], v[8:9], v[108:109]
	v_pk_mul_f32 v[110:111], v[10:11], v[110:111]
	global_store_dwordx4 v123, v[104:107], s[46:47] offset:2048
	global_store_dwordx4 v123, v[108:111], s[46:47] offset:2064
	s_mov_b32 s41, s39
	s_cmp_lt_i32 s41, 0x8000
	s_cbranch_scc0 .Lfn_done
	s_branch .Lfn_step_A
.Lfn_done:
	s_mov_b64 s[38:39], exec
.LBB0_85:
	s_or_b64 exec, exec, s[38:39]
